# grid barrier from the 2nd barrier on: 4 group counters and 4 replicated release counters each on its own 256-byte-spaced line in the unused ws gap after the memset counter (zeroed by WG 0 before its f
# baseline (speedup 1.0000x reference)
; DI void fast_grid_barrier(unsigned* ctr, unsigned target) {
;     asm volatile("s_waitcnt vmcnt(0)" ::: "memory");
;     __syncthreads();
;     if (threadIdx.x == 0) {
;         __builtin_amdgcn_fence(__ATOMIC_RELEASE, "agent");
;         asm volatile("s_waitcnt vmcnt(0)" ::: "memory");
;         __hip_atomic_fetch_add(ctr, 1u, __ATOMIC_RELAXED, __HIP_MEMORY_SCOPE_AGENT);
;         while (__hip_atomic_load(ctr, __ATOMIC_RELAXED, __HIP_MEMORY_SCOPE_AGENT) < target) __builtin_amdgcn_s_sleep(1);
;         __builtin_amdgcn_fence(__ATOMIC_ACQUIRE, "agent");
;         asm volatile("s_waitcnt vmcnt(0)" ::: "memory");
;     }
;     __syncthreads();
; }
.LBB0_4:
	s_cmp_le_i32 s70, s12
	s_cbranch_scc1 .LBB0_26
	v_readlane_b32 s0, v255, 4
	s_cmp_lg_u32 s70, s0
	s_mov_b64 s[0:1], -1
	s_waitcnt vmcnt(0)
	v_readlane_b32 s0, v255, 11
	s_add_i32 s4, s0, 1
	s_barrier
	s_mov_b64 s[0:1], exec
	v_readlane_b32 s6, v255, 12
	v_readlane_b32 s7, v255, 13
	s_and_b64 s[6:7], s[0:1], s[6:7]
	s_mov_b64 exec, s[6:7]
	s_cbranch_execz .LBB0_12
	s_cmp_lg_u32 s4, 1
	s_cbranch_scc1 .Lgb_arrive
	s_cmp_lg_u32 s2, 0
	s_cbranch_scc1 .Lgb_arrive
	v_mov_b32_e32 v1, 0x1000
	global_store_dword v1, v165, s[14:15]
	global_store_dword v1, v165, s[14:15] offset:256
	global_store_dword v1, v165, s[14:15] offset:512
	global_store_dword v1, v165, s[14:15] offset:768
	global_store_dword v1, v165, s[14:15] offset:1024
	global_store_dword v1, v165, s[14:15] offset:1280
	global_store_dword v1, v165, s[14:15] offset:1536
	global_store_dword v1, v165, s[14:15] offset:1792
.Lgb_arrive:
	buffer_wbl2 sc1
	s_waitcnt vmcnt(0)
	s_and_b32 s5, s2, 3
	s_sub_i32 s9, s72, s5
	s_add_i32 s9, s9, 3
	s_lshr_b32 s9, s9, 2
	v_mov_b32_e32 v0, 1
	s_cmp_eq_u32 s4, 1
	s_cbranch_scc1 .Lgb_first
	s_lshl_b32 s8, s5, 8
	s_add_i32 s8, s8, 0x1400
	v_mov_b32_e32 v1, s8
	global_atomic_add v2, v1, v0, s[14:15] sc0
	s_add_i32 s5, s4, -1
	s_mul_i32 s9, s9, s5
	s_lshl_b32 s5, s5, 2
	s_bfe_u32 s8, s2, 0x20002
	s_lshl_b32 s8, s8, 8
	s_add_i32 s8, s8, 0x1000
	s_waitcnt vmcnt(0)
	v_add_u32_e32 v2, 1, v2
	v_cmp_eq_u32_e32 vcc, s9, v2
	s_cbranch_vccz .Lgb_poll2
	v_mov_b32_e32 v1, 0x1000
	global_atomic_add v1, v0, s[14:15]
	global_atomic_add v1, v0, s[14:15] offset:256
	global_atomic_add v1, v0, s[14:15] offset:512
	global_atomic_add v1, v0, s[14:15] offset:768
.Lgb_poll2:
	v_mov_b32_e32 v1, s8
	s_branch .Lgb_poll2_ld

; DI void fast_grid_barrier(unsigned* ctr, unsigned target) {
;     asm volatile("s_waitcnt vmcnt(0)" ::: "memory");
;     __syncthreads();
;     if (threadIdx.x == 0) {
;         __builtin_amdgcn_fence(__ATOMIC_RELEASE, "agent");
;         asm volatile("s_waitcnt vmcnt(0)" ::: "memory");
;         __hip_atomic_fetch_add(ctr, 1u, __ATOMIC_RELAXED, __HIP_MEMORY_SCOPE_AGENT);
;         while (__hip_atomic_load(ctr, __ATOMIC_RELAXED, __HIP_MEMORY_SCOPE_AGENT) < target) __builtin_amdgcn_s_sleep(1);
;         __builtin_amdgcn_fence(__ATOMIC_ACQUIRE, "agent");
;         asm volatile("s_waitcnt vmcnt(0)" ::: "memory");
;     }
;     __syncthreads();
; }
.Lgb_poll2_ld:
	global_load_dword v2, v1, s[14:15] sc1
	s_waitcnt vmcnt(0)
	v_cmp_gt_u32_e32 vcc, s5, v2
	s_cbranch_vccnz .Lgb_poll2_slp
	s_branch .LBB0_11
.Lgb_first:
	s_lshl_b32 s8, s5, 5
	s_add_i32 s8, s8, 0x80
	v_mov_b32_e32 v1, s8
	global_atomic_add v2, v1, v0, s[14:15] sc0
	s_mul_i32 s9, s9, s4
	s_lshl_b32 s5, s4, 2
	s_waitcnt vmcnt(0)
	v_add_u32_e32 v2, 1, v2
	v_cmp_eq_u32_e32 vcc, s9, v2
	s_cbranch_vccz .Lgb_poll
	global_atomic_add v165, v0, s[14:15]
